# plus hand-scheduled 256x128 epilogues (MLP2A/B, OUT1): all loads first, counted waits
# speedup vs baseline: 1.0211x; 1.0036x over previous
.LBB0_50:
	s_sub_u32 s77, s30, 0x1000
	s_lshr_b32 s77, s77, 12
	s_add_u32 s77, s77, 1
	s_cmp_lt_u32 s30, 0x1000
	s_cselect_b32 s77, 0, s77
	s_mul_i32 s77, s77, 0x6000
	s_add_u32 s68, s46, s77
	s_addc_u32 s69, s47, 0
	s_add_u32 s68, s68, 0xfa2e600
	s_addc_u32 s69, s69, 0
	s_lshl_b32 s82, s30, 11
	s_add_u32 s80, s48, s82
	s_addc_u32 s81, s49, 0
	s_lshl_b32 s82, s28, 1
	s_add_u32 s80, s80, s82
	s_addc_u32 s81, s81, 0
	v_and_b32_e32 v0, 31, v200
	v_bfe_u32 v1, v200, 5, 1
	v_lshrrev_b32_e32 v2, 6, v200
	v_and_b32_e32 v68, 1, v2
	v_lshrrev_b32_e32 v69, 1, v2
	v_lshlrev_b32_e32 v70, 6, v68
	v_lshl_or_b32 v70, v1, 2, v70
	v_add_u32_e32 v71, s28, v70
	v_lshlrev_b32_e32 v71, 2, v71
	v_lshl_or_b32 v72, v69, 6, v0
	v_lshlrev_b32_e32 v73, 11, v72
	v_lshl_add_u32 v73, v70, 1, v73
	v_add_u32_e32 v74, 0x10000, v73
	v_lshlrev_b32_e32 v75, 11, v72
	v_lshl_add_u32 v75, v68, 7, v75
	v_lshl_add_u32 v75, v1, 4, v75
	v_add_u32_e32 v69, 0x10000, v75
	global_load_dwordx4 v[76:79], v71, s[44:45]
	global_load_dwordx4 v[80:83], v71, s[44:45] offset:32
	global_load_dwordx4 v[84:87], v71, s[44:45] offset:64
	global_load_dwordx4 v[88:91], v71, s[44:45] offset:96
	global_load_dwordx4 v[92:95], v71, s[44:45] offset:128
	global_load_dwordx4 v[96:99], v71, s[44:45] offset:160
	global_load_dwordx4 v[100:103], v71, s[44:45] offset:192
	global_load_dwordx4 v[104:107], v71, s[44:45] offset:224
	global_load_dwordx4 v[108:111], v71, s[68:69]
	global_load_dwordx4 v[112:115], v71, s[68:69] offset:32
	global_load_dwordx4 v[116:119], v71, s[68:69] offset:64
	global_load_dwordx4 v[120:123], v71, s[68:69] offset:96
	global_load_dwordx4 v[124:127], v71, s[68:69] offset:128
	global_load_dwordx4 v[128:131], v71, s[68:69] offset:160
	global_load_dwordx4 v[132:135], v71, s[68:69] offset:192
	global_load_dwordx4 v[136:139], v71, s[68:69] offset:224
	global_load_dwordx2 v[140:141], v73, s[80:81]
	global_load_dwordx2 v[142:143], v73, s[80:81] offset:16
	global_load_dwordx2 v[144:145], v73, s[80:81] offset:32
	global_load_dwordx2 v[146:147], v73, s[80:81] offset:48
	global_load_dwordx2 v[148:149], v73, s[80:81] offset:64
	global_load_dwordx2 v[150:151], v73, s[80:81] offset:80
	global_load_dwordx2 v[152:153], v73, s[80:81] offset:96
	global_load_dwordx2 v[154:155], v73, s[80:81] offset:112
	global_load_dwordx2 v[156:157], v74, s[80:81]
	global_load_dwordx2 v[158:159], v74, s[80:81] offset:16
	global_load_dwordx2 v[160:161], v74, s[80:81] offset:32
	global_load_dwordx2 v[162:163], v74, s[80:81] offset:48
	global_load_dwordx2 v[164:165], v74, s[80:81] offset:64
	global_load_dwordx2 v[166:167], v74, s[80:81] offset:80
	global_load_dwordx2 v[168:169], v74, s[80:81] offset:96
	global_load_dwordx2 v[170:171], v74, s[80:81] offset:112
	s_waitcnt vmcnt(14)
	v_cvt_f32_f16_e32 v188, v140
	v_cvt_f32_f16_sdwa v189, v140 dst_sel:DWORD dst_unused:UNUSED_PAD src0_sel:WORD_1
	v_cvt_f32_f16_e32 v190, v141
	v_cvt_f32_f16_sdwa v191, v141 dst_sel:DWORD dst_unused:UNUSED_PAD src0_sel:WORD_1
	v_cvt_f32_f16_e32 v192, v142
	v_cvt_f32_f16_sdwa v193, v142 dst_sel:DWORD dst_unused:UNUSED_PAD src0_sel:WORD_1
	v_cvt_f32_f16_e32 v194, v143
	v_cvt_f32_f16_sdwa v195, v143 dst_sel:DWORD dst_unused:UNUSED_PAD src0_sel:WORD_1
	v_pk_add_f32 v[52:53], v[52:53], v[76:77]
	v_pk_add_f32 v[54:55], v[54:55], v[78:79]
	v_pk_add_f32 v[56:57], v[56:57], v[80:81]
	v_pk_add_f32 v[58:59], v[58:59], v[82:83]
	v_pk_mul_f32 v[188:189], v[188:189], s[84:85] op_sel_hi:[1,0]
	v_pk_mul_f32 v[190:191], v[190:191], s[84:85] op_sel_hi:[1,0]
	v_pk_mul_f32 v[192:193], v[192:193], s[84:85] op_sel_hi:[1,0]
	v_pk_mul_f32 v[194:195], v[194:195], s[84:85] op_sel_hi:[1,0]
	v_pk_fma_f32 v[52:53], v[52:53], v[108:109], v[188:189]
	v_pk_fma_f32 v[54:55], v[54:55], v[110:111], v[190:191]
	v_pk_fma_f32 v[56:57], v[56:57], v[112:113], v[192:193]
	v_pk_fma_f32 v[58:59], v[58:59], v[114:115], v[194:195]
	v_cvt_pk_f16_f32 v172, v52, v53
	v_cvt_pk_f16_f32 v173, v54, v55
	v_cvt_pk_f16_f32 v174, v56, v57
	v_cvt_pk_f16_f32 v175, v58, v59
	s_nop 1
	v_permlane32_swap_b32_e32 v172, v174
	v_permlane32_swap_b32_e32 v173, v175
	global_store_dwordx4 v75, v[172:175], s[80:81]
	s_waitcnt vmcnt(13)
	v_cvt_f32_f16_e32 v188, v144
	v_cvt_f32_f16_sdwa v189, v144 dst_sel:DWORD dst_unused:UNUSED_PAD src0_sel:WORD_1
	v_cvt_f32_f16_e32 v190, v145
	v_cvt_f32_f16_sdwa v191, v145 dst_sel:DWORD dst_unused:UNUSED_PAD src0_sel:WORD_1
	v_cvt_f32_f16_e32 v192, v146
	v_cvt_f32_f16_sdwa v193, v146 dst_sel:DWORD dst_unused:UNUSED_PAD src0_sel:WORD_1
	v_cvt_f32_f16_e32 v194, v147
	v_cvt_f32_f16_sdwa v195, v147 dst_sel:DWORD dst_unused:UNUSED_PAD src0_sel:WORD_1
	v_pk_add_f32 v[60:61], v[60:61], v[84:85]
	v_pk_add_f32 v[62:63], v[62:63], v[86:87]
	v_pk_add_f32 v[64:65], v[64:65], v[88:89]
	v_pk_add_f32 v[66:67], v[66:67], v[90:91]
	v_pk_mul_f32 v[188:189], v[188:189], s[84:85] op_sel_hi:[1,0]
	v_pk_mul_f32 v[190:191], v[190:191], s[84:85] op_sel_hi:[1,0]
	v_pk_mul_f32 v[192:193], v[192:193], s[84:85] op_sel_hi:[1,0]
	v_pk_mul_f32 v[194:195], v[194:195], s[84:85] op_sel_hi:[1,0]
	v_pk_fma_f32 v[60:61], v[60:61], v[116:117], v[188:189]
	v_pk_fma_f32 v[62:63], v[62:63], v[118:119], v[190:191]
	v_pk_fma_f32 v[64:65], v[64:65], v[120:121], v[192:193]
	v_pk_fma_f32 v[66:67], v[66:67], v[122:123], v[194:195]
	v_cvt_pk_f16_f32 v184, v60, v61
	v_cvt_pk_f16_f32 v185, v62, v63
	v_cvt_pk_f16_f32 v186, v64, v65
	v_cvt_pk_f16_f32 v187, v66, v67
	s_nop 1
	v_permlane32_swap_b32_e32 v184, v186
	v_permlane32_swap_b32_e32 v185, v187
	global_store_dwordx4 v75, v[184:187], s[80:81] offset:32
	s_waitcnt vmcnt(12)
	v_cvt_f32_f16_e32 v188, v148
	v_cvt_f32_f16_sdwa v189, v148 dst_sel:DWORD dst_unused:UNUSED_PAD src0_sel:WORD_1
	v_cvt_f32_f16_e32 v190, v149
	v_cvt_f32_f16_sdwa v191, v149 dst_sel:DWORD dst_unused:UNUSED_PAD src0_sel:WORD_1
	v_cvt_f32_f16_e32 v192, v150
	v_cvt_f32_f16_sdwa v193, v150 dst_sel:DWORD dst_unused:UNUSED_PAD src0_sel:WORD_1
	v_cvt_f32_f16_e32 v194, v151
	v_cvt_f32_f16_sdwa v195, v151 dst_sel:DWORD dst_unused:UNUSED_PAD src0_sel:WORD_1
	v_pk_add_f32 v[36:37], v[36:37], v[92:93]
	v_pk_add_f32 v[38:39], v[38:39], v[94:95]
	v_pk_add_f32 v[40:41], v[40:41], v[96:97]
	v_pk_add_f32 v[42:43], v[42:43], v[98:99]
	v_pk_mul_f32 v[188:189], v[188:189], s[84:85] op_sel_hi:[1,0]
	v_pk_mul_f32 v[190:191], v[190:191], s[84:85] op_sel_hi:[1,0]
	v_pk_mul_f32 v[192:193], v[192:193], s[84:85] op_sel_hi:[1,0]
	v_pk_mul_f32 v[194:195], v[194:195], s[84:85] op_sel_hi:[1,0]
	v_pk_fma_f32 v[36:37], v[36:37], v[124:125], v[188:189]
	v_pk_fma_f32 v[38:39], v[38:39], v[126:127], v[190:191]
	v_pk_fma_f32 v[40:41], v[40:41], v[128:129], v[192:193]
	v_pk_fma_f32 v[42:43], v[42:43], v[130:131], v[194:195]
	v_cvt_pk_f16_f32 v172, v36, v37
	v_cvt_pk_f16_f32 v173, v38, v39
	v_cvt_pk_f16_f32 v174, v40, v41
	v_cvt_pk_f16_f32 v175, v42, v43
	s_nop 1
	v_permlane32_swap_b32_e32 v172, v174
	v_permlane32_swap_b32_e32 v173, v175
	global_store_dwordx4 v75, v[172:175], s[80:81] offset:64
	s_waitcnt vmcnt(11)
	v_cvt_f32_f16_e32 v188, v152
	v_cvt_f32_f16_sdwa v189, v152 dst_sel:DWORD dst_unused:UNUSED_PAD src0_sel:WORD_1
	v_cvt_f32_f16_e32 v190, v153
	v_cvt_f32_f16_sdwa v191, v153 dst_sel:DWORD dst_unused:UNUSED_PAD src0_sel:WORD_1
	v_cvt_f32_f16_e32 v192, v154
	v_cvt_f32_f16_sdwa v193, v154 dst_sel:DWORD dst_unused:UNUSED_PAD src0_sel:WORD_1
	v_cvt_f32_f16_e32 v194, v155
	v_cvt_f32_f16_sdwa v195, v155 dst_sel:DWORD dst_unused:UNUSED_PAD src0_sel:WORD_1
	v_pk_add_f32 v[44:45], v[44:45], v[100:101]
	v_pk_add_f32 v[46:47], v[46:47], v[102:103]
	v_pk_add_f32 v[48:49], v[48:49], v[104:105]
	v_pk_add_f32 v[50:51], v[50:51], v[106:107]
	v_pk_mul_f32 v[188:189], v[188:189], s[84:85] op_sel_hi:[1,0]
	v_pk_mul_f32 v[190:191], v[190:191], s[84:85] op_sel_hi:[1,0]
	v_pk_mul_f32 v[192:193], v[192:193], s[84:85] op_sel_hi:[1,0]
	v_pk_mul_f32 v[194:195], v[194:195], s[84:85] op_sel_hi:[1,0]
	v_pk_fma_f32 v[44:45], v[44:45], v[132:133], v[188:189]
	v_pk_fma_f32 v[46:47], v[46:47], v[134:135], v[190:191]
	v_pk_fma_f32 v[48:49], v[48:49], v[136:137], v[192:193]
	v_pk_fma_f32 v[50:51], v[50:51], v[138:139], v[194:195]
	v_cvt_pk_f16_f32 v184, v44, v45
	v_cvt_pk_f16_f32 v185, v46, v47
	v_cvt_pk_f16_f32 v186, v48, v49
	v_cvt_pk_f16_f32 v187, v50, v51
	s_nop 1
	v_permlane32_swap_b32_e32 v184, v186
	v_permlane32_swap_b32_e32 v185, v187
	global_store_dwordx4 v75, v[184:187], s[80:81] offset:96
	s_waitcnt vmcnt(10)
	v_cvt_f32_f16_e32 v188, v156
	v_cvt_f32_f16_sdwa v189, v156 dst_sel:DWORD dst_unused:UNUSED_PAD src0_sel:WORD_1
	v_cvt_f32_f16_e32 v190, v157
	v_cvt_f32_f16_sdwa v191, v157 dst_sel:DWORD dst_unused:UNUSED_PAD src0_sel:WORD_1
	v_cvt_f32_f16_e32 v192, v158
	v_cvt_f32_f16_sdwa v193, v158 dst_sel:DWORD dst_unused:UNUSED_PAD src0_sel:WORD_1
	v_cvt_f32_f16_e32 v194, v159
	v_cvt_f32_f16_sdwa v195, v159 dst_sel:DWORD dst_unused:UNUSED_PAD src0_sel:WORD_1
	v_pk_add_f32 v[20:21], v[20:21], v[76:77]
	v_pk_add_f32 v[22:23], v[22:23], v[78:79]
	v_pk_add_f32 v[24:25], v[24:25], v[80:81]
	v_pk_add_f32 v[26:27], v[26:27], v[82:83]
	v_pk_mul_f32 v[188:189], v[188:189], s[84:85] op_sel_hi:[1,0]
	v_pk_mul_f32 v[190:191], v[190:191], s[84:85] op_sel_hi:[1,0]
	v_pk_mul_f32 v[192:193], v[192:193], s[84:85] op_sel_hi:[1,0]
	v_pk_mul_f32 v[194:195], v[194:195], s[84:85] op_sel_hi:[1,0]
	v_pk_fma_f32 v[20:21], v[20:21], v[108:109], v[188:189]
	v_pk_fma_f32 v[22:23], v[22:23], v[110:111], v[190:191]
	v_pk_fma_f32 v[24:25], v[24:25], v[112:113], v[192:193]
	v_pk_fma_f32 v[26:27], v[26:27], v[114:115], v[194:195]
	v_cvt_pk_f16_f32 v172, v20, v21
	v_cvt_pk_f16_f32 v173, v22, v23
	v_cvt_pk_f16_f32 v174, v24, v25
	v_cvt_pk_f16_f32 v175, v26, v27
	s_nop 1
	v_permlane32_swap_b32_e32 v172, v174
	v_permlane32_swap_b32_e32 v173, v175
	global_store_dwordx4 v69, v[172:175], s[80:81]
	s_waitcnt vmcnt(9)
	v_cvt_f32_f16_e32 v188, v160
	v_cvt_f32_f16_sdwa v189, v160 dst_sel:DWORD dst_unused:UNUSED_PAD src0_sel:WORD_1
	v_cvt_f32_f16_e32 v190, v161
	v_cvt_f32_f16_sdwa v191, v161 dst_sel:DWORD dst_unused:UNUSED_PAD src0_sel:WORD_1
	v_cvt_f32_f16_e32 v192, v162
	v_cvt_f32_f16_sdwa v193, v162 dst_sel:DWORD dst_unused:UNUSED_PAD src0_sel:WORD_1
	v_cvt_f32_f16_e32 v194, v163
	v_cvt_f32_f16_sdwa v195, v163 dst_sel:DWORD dst_unused:UNUSED_PAD src0_sel:WORD_1
	v_pk_add_f32 v[28:29], v[28:29], v[84:85]
	v_pk_add_f32 v[30:31], v[30:31], v[86:87]
	v_pk_add_f32 v[32:33], v[32:33], v[88:89]
	v_pk_add_f32 v[34:35], v[34:35], v[90:91]
	v_pk_mul_f32 v[188:189], v[188:189], s[84:85] op_sel_hi:[1,0]
	v_pk_mul_f32 v[190:191], v[190:191], s[84:85] op_sel_hi:[1,0]
	v_pk_mul_f32 v[192:193], v[192:193], s[84:85] op_sel_hi:[1,0]
	v_pk_mul_f32 v[194:195], v[194:195], s[84:85] op_sel_hi:[1,0]
	v_pk_fma_f32 v[28:29], v[28:29], v[116:117], v[188:189]
	v_pk_fma_f32 v[30:31], v[30:31], v[118:119], v[190:191]
	v_pk_fma_f32 v[32:33], v[32:33], v[120:121], v[192:193]
	v_pk_fma_f32 v[34:35], v[34:35], v[122:123], v[194:195]
	v_cvt_pk_f16_f32 v184, v28, v29
	v_cvt_pk_f16_f32 v185, v30, v31
	v_cvt_pk_f16_f32 v186, v32, v33
	v_cvt_pk_f16_f32 v187, v34, v35
	s_nop 1
	v_permlane32_swap_b32_e32 v184, v186
	v_permlane32_swap_b32_e32 v185, v187
	global_store_dwordx4 v69, v[184:187], s[80:81] offset:32
	s_waitcnt vmcnt(8)
	v_cvt_f32_f16_e32 v188, v164
	v_cvt_f32_f16_sdwa v189, v164 dst_sel:DWORD dst_unused:UNUSED_PAD src0_sel:WORD_1
	v_cvt_f32_f16_e32 v190, v165
	v_cvt_f32_f16_sdwa v191, v165 dst_sel:DWORD dst_unused:UNUSED_PAD src0_sel:WORD_1
	v_cvt_f32_f16_e32 v192, v166
	v_cvt_f32_f16_sdwa v193, v166 dst_sel:DWORD dst_unused:UNUSED_PAD src0_sel:WORD_1
	v_cvt_f32_f16_e32 v194, v167
	v_cvt_f32_f16_sdwa v195, v167 dst_sel:DWORD dst_unused:UNUSED_PAD src0_sel:WORD_1
	v_pk_add_f32 v[4:5], v[4:5], v[92:93]
	v_pk_add_f32 v[6:7], v[6:7], v[94:95]
	v_pk_add_f32 v[8:9], v[8:9], v[96:97]
	v_pk_add_f32 v[10:11], v[10:11], v[98:99]
	v_pk_mul_f32 v[188:189], v[188:189], s[84:85] op_sel_hi:[1,0]
	v_pk_mul_f32 v[190:191], v[190:191], s[84:85] op_sel_hi:[1,0]
	v_pk_mul_f32 v[192:193], v[192:193], s[84:85] op_sel_hi:[1,0]
	v_pk_mul_f32 v[194:195], v[194:195], s[84:85] op_sel_hi:[1,0]
	v_pk_fma_f32 v[4:5], v[4:5], v[124:125], v[188:189]
	v_pk_fma_f32 v[6:7], v[6:7], v[126:127], v[190:191]
	v_pk_fma_f32 v[8:9], v[8:9], v[128:129], v[192:193]
	v_pk_fma_f32 v[10:11], v[10:11], v[130:131], v[194:195]
	v_cvt_pk_f16_f32 v172, v4, v5
	v_cvt_pk_f16_f32 v173, v6, v7
	v_cvt_pk_f16_f32 v174, v8, v9
	v_cvt_pk_f16_f32 v175, v10, v11
	s_nop 1
	v_permlane32_swap_b32_e32 v172, v174
	v_permlane32_swap_b32_e32 v173, v175
	global_store_dwordx4 v69, v[172:175], s[80:81] offset:64
	s_waitcnt vmcnt(7)
	v_cvt_f32_f16_e32 v188, v168
	v_cvt_f32_f16_sdwa v189, v168 dst_sel:DWORD dst_unused:UNUSED_PAD src0_sel:WORD_1
	v_cvt_f32_f16_e32 v190, v169
	v_cvt_f32_f16_sdwa v191, v169 dst_sel:DWORD dst_unused:UNUSED_PAD src0_sel:WORD_1
	v_cvt_f32_f16_e32 v192, v170
	v_cvt_f32_f16_sdwa v193, v170 dst_sel:DWORD dst_unused:UNUSED_PAD src0_sel:WORD_1
	v_cvt_f32_f16_e32 v194, v171
	v_cvt_f32_f16_sdwa v195, v171 dst_sel:DWORD dst_unused:UNUSED_PAD src0_sel:WORD_1
	v_pk_add_f32 v[12:13], v[12:13], v[100:101]
	v_pk_add_f32 v[14:15], v[14:15], v[102:103]
	v_pk_add_f32 v[16:17], v[16:17], v[104:105]
	v_pk_add_f32 v[18:19], v[18:19], v[106:107]
	v_pk_mul_f32 v[188:189], v[188:189], s[84:85] op_sel_hi:[1,0]
	v_pk_mul_f32 v[190:191], v[190:191], s[84:85] op_sel_hi:[1,0]
	v_pk_mul_f32 v[192:193], v[192:193], s[84:85] op_sel_hi:[1,0]
	v_pk_mul_f32 v[194:195], v[194:195], s[84:85] op_sel_hi:[1,0]
	v_pk_fma_f32 v[12:13], v[12:13], v[132:133], v[188:189]
	v_pk_fma_f32 v[14:15], v[14:15], v[134:135], v[190:191]
	v_pk_fma_f32 v[16:17], v[16:17], v[136:137], v[192:193]
	v_pk_fma_f32 v[18:19], v[18:19], v[138:139], v[194:195]
	v_cvt_pk_f16_f32 v184, v12, v13
	v_cvt_pk_f16_f32 v185, v14, v15
	v_cvt_pk_f16_f32 v186, v16, v17
	v_cvt_pk_f16_f32 v187, v18, v19
	s_nop 1
	v_permlane32_swap_b32_e32 v184, v186
	v_permlane32_swap_b32_e32 v185, v187
	global_store_dwordx4 v69, v[184:187], s[80:81] offset:96
	s_mov_b64 s[30:31], 0xfa10600
	s_ashr_i32 s29, s28, 31
	s_lshl_b64 s[28:29], s[28:29], 1
	s_add_i32 s24, s24, s64
	s_cmpk_gt_i32 s24, 0x27f
	s_cbranch_scc1 .LBB0_67

.LBB0_163:
	s_sub_u32 s77, s25, 0x1000
	s_lshr_b32 s77, s77, 12
	s_add_u32 s77, s77, 1
	s_cmp_lt_u32 s25, 0x1000
	s_cselect_b32 s77, 0, s77
	s_mul_i32 s77, s77, 0x6000
	s_add_u32 s68, s28, s77
	s_addc_u32 s69, s29, 0
	s_add_u32 s68, s68, 0x20000
	s_addc_u32 s69, s69, 0
	s_lshl_b32 s82, s25, 11
	s_add_u32 s80, s46, s82
	s_addc_u32 s81, s47, 0
	s_lshl_b32 s82, s30, 1
	s_add_u32 s80, s80, s82
	s_addc_u32 s81, s81, 0
	v_and_b32_e32 v0, 31, v200
	v_bfe_u32 v1, v200, 5, 1
	v_lshrrev_b32_e32 v2, 6, v200
	v_and_b32_e32 v68, 1, v2
	v_lshrrev_b32_e32 v69, 1, v2
	v_lshlrev_b32_e32 v70, 6, v68
	v_lshl_or_b32 v70, v1, 2, v70
	v_add_u32_e32 v71, s30, v70
	v_lshlrev_b32_e32 v71, 2, v71
	v_lshl_or_b32 v72, v69, 6, v0
	v_lshlrev_b32_e32 v73, 11, v72
	v_lshl_add_u32 v73, v70, 1, v73
	v_add_u32_e32 v74, 0x10000, v73
	v_lshlrev_b32_e32 v75, 11, v72
	v_lshl_add_u32 v75, v68, 7, v75
	v_lshl_add_u32 v75, v1, 4, v75
	v_add_u32_e32 v69, 0x10000, v75
	global_load_dwordx4 v[76:79], v71, s[42:43]
	global_load_dwordx4 v[80:83], v71, s[42:43] offset:32
	global_load_dwordx4 v[84:87], v71, s[42:43] offset:64
	global_load_dwordx4 v[88:91], v71, s[42:43] offset:96
	global_load_dwordx4 v[92:95], v71, s[42:43] offset:128
	global_load_dwordx4 v[96:99], v71, s[42:43] offset:160
	global_load_dwordx4 v[100:103], v71, s[42:43] offset:192
	global_load_dwordx4 v[104:107], v71, s[42:43] offset:224
	global_load_dwordx4 v[108:111], v71, s[68:69]
	global_load_dwordx4 v[112:115], v71, s[68:69] offset:32
	global_load_dwordx4 v[116:119], v71, s[68:69] offset:64
	global_load_dwordx4 v[120:123], v71, s[68:69] offset:96
	global_load_dwordx4 v[124:127], v71, s[68:69] offset:128
	global_load_dwordx4 v[128:131], v71, s[68:69] offset:160
	global_load_dwordx4 v[132:135], v71, s[68:69] offset:192
	global_load_dwordx4 v[136:139], v71, s[68:69] offset:224
	global_load_dwordx2 v[140:141], v73, s[80:81]
	global_load_dwordx2 v[142:143], v73, s[80:81] offset:16
	global_load_dwordx2 v[144:145], v73, s[80:81] offset:32
	global_load_dwordx2 v[146:147], v73, s[80:81] offset:48
	global_load_dwordx2 v[148:149], v73, s[80:81] offset:64
	global_load_dwordx2 v[150:151], v73, s[80:81] offset:80
	global_load_dwordx2 v[152:153], v73, s[80:81] offset:96
	global_load_dwordx2 v[154:155], v73, s[80:81] offset:112
	global_load_dwordx2 v[156:157], v74, s[80:81]
	global_load_dwordx2 v[158:159], v74, s[80:81] offset:16
	global_load_dwordx2 v[160:161], v74, s[80:81] offset:32
	global_load_dwordx2 v[162:163], v74, s[80:81] offset:48
	global_load_dwordx2 v[164:165], v74, s[80:81] offset:64
	global_load_dwordx2 v[166:167], v74, s[80:81] offset:80
	global_load_dwordx2 v[168:169], v74, s[80:81] offset:96
	global_load_dwordx2 v[170:171], v74, s[80:81] offset:112
	s_waitcnt vmcnt(14)
	v_cvt_f32_f16_e32 v188, v140
	v_cvt_f32_f16_sdwa v189, v140 dst_sel:DWORD dst_unused:UNUSED_PAD src0_sel:WORD_1
	v_cvt_f32_f16_e32 v190, v141
	v_cvt_f32_f16_sdwa v191, v141 dst_sel:DWORD dst_unused:UNUSED_PAD src0_sel:WORD_1
	v_cvt_f32_f16_e32 v192, v142
	v_cvt_f32_f16_sdwa v193, v142 dst_sel:DWORD dst_unused:UNUSED_PAD src0_sel:WORD_1
	v_cvt_f32_f16_e32 v194, v143
	v_cvt_f32_f16_sdwa v195, v143 dst_sel:DWORD dst_unused:UNUSED_PAD src0_sel:WORD_1
	v_pk_add_f32 v[52:53], v[52:53], v[76:77]
	v_pk_add_f32 v[54:55], v[54:55], v[78:79]
	v_pk_add_f32 v[56:57], v[56:57], v[80:81]
	v_pk_add_f32 v[58:59], v[58:59], v[82:83]
	v_pk_mul_f32 v[188:189], v[188:189], s[84:85] op_sel_hi:[1,0]
	v_pk_mul_f32 v[190:191], v[190:191], s[84:85] op_sel_hi:[1,0]
	v_pk_mul_f32 v[192:193], v[192:193], s[84:85] op_sel_hi:[1,0]
	v_pk_mul_f32 v[194:195], v[194:195], s[84:85] op_sel_hi:[1,0]
	v_pk_fma_f32 v[52:53], v[52:53], v[108:109], v[188:189]
	v_pk_fma_f32 v[54:55], v[54:55], v[110:111], v[190:191]
	v_pk_fma_f32 v[56:57], v[56:57], v[112:113], v[192:193]
	v_pk_fma_f32 v[58:59], v[58:59], v[114:115], v[194:195]
	v_cvt_pk_f16_f32 v172, v52, v53
	v_cvt_pk_f16_f32 v173, v54, v55
	v_cvt_pk_f16_f32 v174, v56, v57
	v_cvt_pk_f16_f32 v175, v58, v59
	s_nop 1
	v_permlane32_swap_b32_e32 v172, v174
	v_permlane32_swap_b32_e32 v173, v175
	global_store_dwordx4 v75, v[172:175], s[80:81]
	s_waitcnt vmcnt(13)
	v_cvt_f32_f16_e32 v188, v144
	v_cvt_f32_f16_sdwa v189, v144 dst_sel:DWORD dst_unused:UNUSED_PAD src0_sel:WORD_1
	v_cvt_f32_f16_e32 v190, v145
	v_cvt_f32_f16_sdwa v191, v145 dst_sel:DWORD dst_unused:UNUSED_PAD src0_sel:WORD_1
	v_cvt_f32_f16_e32 v192, v146
	v_cvt_f32_f16_sdwa v193, v146 dst_sel:DWORD dst_unused:UNUSED_PAD src0_sel:WORD_1
	v_cvt_f32_f16_e32 v194, v147
	v_cvt_f32_f16_sdwa v195, v147 dst_sel:DWORD dst_unused:UNUSED_PAD src0_sel:WORD_1
	v_pk_add_f32 v[60:61], v[60:61], v[84:85]
	v_pk_add_f32 v[62:63], v[62:63], v[86:87]
	v_pk_add_f32 v[64:65], v[64:65], v[88:89]
	v_pk_add_f32 v[66:67], v[66:67], v[90:91]
	v_pk_mul_f32 v[188:189], v[188:189], s[84:85] op_sel_hi:[1,0]
	v_pk_mul_f32 v[190:191], v[190:191], s[84:85] op_sel_hi:[1,0]
	v_pk_mul_f32 v[192:193], v[192:193], s[84:85] op_sel_hi:[1,0]
	v_pk_mul_f32 v[194:195], v[194:195], s[84:85] op_sel_hi:[1,0]
	v_pk_fma_f32 v[60:61], v[60:61], v[116:117], v[188:189]
	v_pk_fma_f32 v[62:63], v[62:63], v[118:119], v[190:191]
	v_pk_fma_f32 v[64:65], v[64:65], v[120:121], v[192:193]
	v_pk_fma_f32 v[66:67], v[66:67], v[122:123], v[194:195]
	v_cvt_pk_f16_f32 v184, v60, v61
	v_cvt_pk_f16_f32 v185, v62, v63
	v_cvt_pk_f16_f32 v186, v64, v65
	v_cvt_pk_f16_f32 v187, v66, v67
	s_nop 1
	v_permlane32_swap_b32_e32 v184, v186
	v_permlane32_swap_b32_e32 v185, v187
	global_store_dwordx4 v75, v[184:187], s[80:81] offset:32
	s_waitcnt vmcnt(12)
	v_cvt_f32_f16_e32 v188, v148
	v_cvt_f32_f16_sdwa v189, v148 dst_sel:DWORD dst_unused:UNUSED_PAD src0_sel:WORD_1
	v_cvt_f32_f16_e32 v190, v149
	v_cvt_f32_f16_sdwa v191, v149 dst_sel:DWORD dst_unused:UNUSED_PAD src0_sel:WORD_1
	v_cvt_f32_f16_e32 v192, v150
	v_cvt_f32_f16_sdwa v193, v150 dst_sel:DWORD dst_unused:UNUSED_PAD src0_sel:WORD_1
	v_cvt_f32_f16_e32 v194, v151
	v_cvt_f32_f16_sdwa v195, v151 dst_sel:DWORD dst_unused:UNUSED_PAD src0_sel:WORD_1
	v_pk_add_f32 v[36:37], v[36:37], v[92:93]
	v_pk_add_f32 v[38:39], v[38:39], v[94:95]
	v_pk_add_f32 v[40:41], v[40:41], v[96:97]
	v_pk_add_f32 v[42:43], v[42:43], v[98:99]
	v_pk_mul_f32 v[188:189], v[188:189], s[84:85] op_sel_hi:[1,0]
	v_pk_mul_f32 v[190:191], v[190:191], s[84:85] op_sel_hi:[1,0]
	v_pk_mul_f32 v[192:193], v[192:193], s[84:85] op_sel_hi:[1,0]
	v_pk_mul_f32 v[194:195], v[194:195], s[84:85] op_sel_hi:[1,0]
	v_pk_fma_f32 v[36:37], v[36:37], v[124:125], v[188:189]
	v_pk_fma_f32 v[38:39], v[38:39], v[126:127], v[190:191]
	v_pk_fma_f32 v[40:41], v[40:41], v[128:129], v[192:193]
	v_pk_fma_f32 v[42:43], v[42:43], v[130:131], v[194:195]
	v_cvt_pk_f16_f32 v172, v36, v37
	v_cvt_pk_f16_f32 v173, v38, v39
	v_cvt_pk_f16_f32 v174, v40, v41
	v_cvt_pk_f16_f32 v175, v42, v43
	s_nop 1
	v_permlane32_swap_b32_e32 v172, v174
	v_permlane32_swap_b32_e32 v173, v175
	global_store_dwordx4 v75, v[172:175], s[80:81] offset:64
	s_waitcnt vmcnt(11)
	v_cvt_f32_f16_e32 v188, v152
	v_cvt_f32_f16_sdwa v189, v152 dst_sel:DWORD dst_unused:UNUSED_PAD src0_sel:WORD_1
	v_cvt_f32_f16_e32 v190, v153
	v_cvt_f32_f16_sdwa v191, v153 dst_sel:DWORD dst_unused:UNUSED_PAD src0_sel:WORD_1
	v_cvt_f32_f16_e32 v192, v154
	v_cvt_f32_f16_sdwa v193, v154 dst_sel:DWORD dst_unused:UNUSED_PAD src0_sel:WORD_1
	v_cvt_f32_f16_e32 v194, v155
	v_cvt_f32_f16_sdwa v195, v155 dst_sel:DWORD dst_unused:UNUSED_PAD src0_sel:WORD_1
	v_pk_add_f32 v[44:45], v[44:45], v[100:101]
	v_pk_add_f32 v[46:47], v[46:47], v[102:103]
	v_pk_add_f32 v[48:49], v[48:49], v[104:105]
	v_pk_add_f32 v[50:51], v[50:51], v[106:107]
	v_pk_mul_f32 v[188:189], v[188:189], s[84:85] op_sel_hi:[1,0]
	v_pk_mul_f32 v[190:191], v[190:191], s[84:85] op_sel_hi:[1,0]
	v_pk_mul_f32 v[192:193], v[192:193], s[84:85] op_sel_hi:[1,0]
	v_pk_mul_f32 v[194:195], v[194:195], s[84:85] op_sel_hi:[1,0]
	v_pk_fma_f32 v[44:45], v[44:45], v[132:133], v[188:189]
	v_pk_fma_f32 v[46:47], v[46:47], v[134:135], v[190:191]
	v_pk_fma_f32 v[48:49], v[48:49], v[136:137], v[192:193]
	v_pk_fma_f32 v[50:51], v[50:51], v[138:139], v[194:195]
	v_cvt_pk_f16_f32 v184, v44, v45
	v_cvt_pk_f16_f32 v185, v46, v47
	v_cvt_pk_f16_f32 v186, v48, v49
	v_cvt_pk_f16_f32 v187, v50, v51
	s_nop 1
	v_permlane32_swap_b32_e32 v184, v186
	v_permlane32_swap_b32_e32 v185, v187
	global_store_dwordx4 v75, v[184:187], s[80:81] offset:96
	s_waitcnt vmcnt(10)
	v_cvt_f32_f16_e32 v188, v156
	v_cvt_f32_f16_sdwa v189, v156 dst_sel:DWORD dst_unused:UNUSED_PAD src0_sel:WORD_1
	v_cvt_f32_f16_e32 v190, v157
	v_cvt_f32_f16_sdwa v191, v157 dst_sel:DWORD dst_unused:UNUSED_PAD src0_sel:WORD_1
	v_cvt_f32_f16_e32 v192, v158
	v_cvt_f32_f16_sdwa v193, v158 dst_sel:DWORD dst_unused:UNUSED_PAD src0_sel:WORD_1
	v_cvt_f32_f16_e32 v194, v159
	v_cvt_f32_f16_sdwa v195, v159 dst_sel:DWORD dst_unused:UNUSED_PAD src0_sel:WORD_1
	v_pk_add_f32 v[20:21], v[20:21], v[76:77]
	v_pk_add_f32 v[22:23], v[22:23], v[78:79]
	v_pk_add_f32 v[24:25], v[24:25], v[80:81]
	v_pk_add_f32 v[26:27], v[26:27], v[82:83]
	v_pk_mul_f32 v[188:189], v[188:189], s[84:85] op_sel_hi:[1,0]
	v_pk_mul_f32 v[190:191], v[190:191], s[84:85] op_sel_hi:[1,0]
	v_pk_mul_f32 v[192:193], v[192:193], s[84:85] op_sel_hi:[1,0]
	v_pk_mul_f32 v[194:195], v[194:195], s[84:85] op_sel_hi:[1,0]
	v_pk_fma_f32 v[20:21], v[20:21], v[108:109], v[188:189]
	v_pk_fma_f32 v[22:23], v[22:23], v[110:111], v[190:191]
	v_pk_fma_f32 v[24:25], v[24:25], v[112:113], v[192:193]
	v_pk_fma_f32 v[26:27], v[26:27], v[114:115], v[194:195]
	v_cvt_pk_f16_f32 v172, v20, v21
	v_cvt_pk_f16_f32 v173, v22, v23
	v_cvt_pk_f16_f32 v174, v24, v25
	v_cvt_pk_f16_f32 v175, v26, v27
	s_nop 1
	v_permlane32_swap_b32_e32 v172, v174
	v_permlane32_swap_b32_e32 v173, v175
	global_store_dwordx4 v69, v[172:175], s[80:81]
	s_waitcnt vmcnt(9)
	v_cvt_f32_f16_e32 v188, v160
	v_cvt_f32_f16_sdwa v189, v160 dst_sel:DWORD dst_unused:UNUSED_PAD src0_sel:WORD_1
	v_cvt_f32_f16_e32 v190, v161
	v_cvt_f32_f16_sdwa v191, v161 dst_sel:DWORD dst_unused:UNUSED_PAD src0_sel:WORD_1
	v_cvt_f32_f16_e32 v192, v162
	v_cvt_f32_f16_sdwa v193, v162 dst_sel:DWORD dst_unused:UNUSED_PAD src0_sel:WORD_1
	v_cvt_f32_f16_e32 v194, v163
	v_cvt_f32_f16_sdwa v195, v163 dst_sel:DWORD dst_unused:UNUSED_PAD src0_sel:WORD_1
	v_pk_add_f32 v[28:29], v[28:29], v[84:85]
	v_pk_add_f32 v[30:31], v[30:31], v[86:87]
	v_pk_add_f32 v[32:33], v[32:33], v[88:89]
	v_pk_add_f32 v[34:35], v[34:35], v[90:91]
	v_pk_mul_f32 v[188:189], v[188:189], s[84:85] op_sel_hi:[1,0]
	v_pk_mul_f32 v[190:191], v[190:191], s[84:85] op_sel_hi:[1,0]
	v_pk_mul_f32 v[192:193], v[192:193], s[84:85] op_sel_hi:[1,0]
	v_pk_mul_f32 v[194:195], v[194:195], s[84:85] op_sel_hi:[1,0]
	v_pk_fma_f32 v[28:29], v[28:29], v[116:117], v[188:189]
	v_pk_fma_f32 v[30:31], v[30:31], v[118:119], v[190:191]
	v_pk_fma_f32 v[32:33], v[32:33], v[120:121], v[192:193]
	v_pk_fma_f32 v[34:35], v[34:35], v[122:123], v[194:195]
	v_cvt_pk_f16_f32 v184, v28, v29
	v_cvt_pk_f16_f32 v185, v30, v31
	v_cvt_pk_f16_f32 v186, v32, v33
	v_cvt_pk_f16_f32 v187, v34, v35
	s_nop 1
	v_permlane32_swap_b32_e32 v184, v186
	v_permlane32_swap_b32_e32 v185, v187
	global_store_dwordx4 v69, v[184:187], s[80:81] offset:32
	s_waitcnt vmcnt(8)
	v_cvt_f32_f16_e32 v188, v164
	v_cvt_f32_f16_sdwa v189, v164 dst_sel:DWORD dst_unused:UNUSED_PAD src0_sel:WORD_1
	v_cvt_f32_f16_e32 v190, v165
	v_cvt_f32_f16_sdwa v191, v165 dst_sel:DWORD dst_unused:UNUSED_PAD src0_sel:WORD_1
	v_cvt_f32_f16_e32 v192, v166
	v_cvt_f32_f16_sdwa v193, v166 dst_sel:DWORD dst_unused:UNUSED_PAD src0_sel:WORD_1
	v_cvt_f32_f16_e32 v194, v167
	v_cvt_f32_f16_sdwa v195, v167 dst_sel:DWORD dst_unused:UNUSED_PAD src0_sel:WORD_1
	v_pk_add_f32 v[4:5], v[4:5], v[92:93]
	v_pk_add_f32 v[6:7], v[6:7], v[94:95]
	v_pk_add_f32 v[8:9], v[8:9], v[96:97]
	v_pk_add_f32 v[10:11], v[10:11], v[98:99]
	v_pk_mul_f32 v[188:189], v[188:189], s[84:85] op_sel_hi:[1,0]
	v_pk_mul_f32 v[190:191], v[190:191], s[84:85] op_sel_hi:[1,0]
	v_pk_mul_f32 v[192:193], v[192:193], s[84:85] op_sel_hi:[1,0]
	v_pk_mul_f32 v[194:195], v[194:195], s[84:85] op_sel_hi:[1,0]
	v_pk_fma_f32 v[4:5], v[4:5], v[124:125], v[188:189]
	v_pk_fma_f32 v[6:7], v[6:7], v[126:127], v[190:191]
	v_pk_fma_f32 v[8:9], v[8:9], v[128:129], v[192:193]
	v_pk_fma_f32 v[10:11], v[10:11], v[130:131], v[194:195]
	v_cvt_pk_f16_f32 v172, v4, v5
	v_cvt_pk_f16_f32 v173, v6, v7
	v_cvt_pk_f16_f32 v174, v8, v9
	v_cvt_pk_f16_f32 v175, v10, v11
	s_nop 1
	v_permlane32_swap_b32_e32 v172, v174
	v_permlane32_swap_b32_e32 v173, v175
	global_store_dwordx4 v69, v[172:175], s[80:81] offset:64
	s_waitcnt vmcnt(7)
	v_cvt_f32_f16_e32 v188, v168
	v_cvt_f32_f16_sdwa v189, v168 dst_sel:DWORD dst_unused:UNUSED_PAD src0_sel:WORD_1
	v_cvt_f32_f16_e32 v190, v169
	v_cvt_f32_f16_sdwa v191, v169 dst_sel:DWORD dst_unused:UNUSED_PAD src0_sel:WORD_1
	v_cvt_f32_f16_e32 v192, v170
	v_cvt_f32_f16_sdwa v193, v170 dst_sel:DWORD dst_unused:UNUSED_PAD src0_sel:WORD_1
	v_cvt_f32_f16_e32 v194, v171
	v_cvt_f32_f16_sdwa v195, v171 dst_sel:DWORD dst_unused:UNUSED_PAD src0_sel:WORD_1
	v_pk_add_f32 v[12:13], v[12:13], v[100:101]
	v_pk_add_f32 v[14:15], v[14:15], v[102:103]
	v_pk_add_f32 v[16:17], v[16:17], v[104:105]
	v_pk_add_f32 v[18:19], v[18:19], v[106:107]
	v_pk_mul_f32 v[188:189], v[188:189], s[84:85] op_sel_hi:[1,0]
	v_pk_mul_f32 v[190:191], v[190:191], s[84:85] op_sel_hi:[1,0]
	v_pk_mul_f32 v[192:193], v[192:193], s[84:85] op_sel_hi:[1,0]
	v_pk_mul_f32 v[194:195], v[194:195], s[84:85] op_sel_hi:[1,0]
	v_pk_fma_f32 v[12:13], v[12:13], v[132:133], v[188:189]
	v_pk_fma_f32 v[14:15], v[14:15], v[134:135], v[190:191]
	v_pk_fma_f32 v[16:17], v[16:17], v[136:137], v[192:193]
	v_pk_fma_f32 v[18:19], v[18:19], v[138:139], v[194:195]
	v_cvt_pk_f16_f32 v184, v12, v13
	v_cvt_pk_f16_f32 v185, v14, v15
	v_cvt_pk_f16_f32 v186, v16, v17
	v_cvt_pk_f16_f32 v187, v18, v19
	s_nop 1
	v_permlane32_swap_b32_e32 v184, v186
	v_permlane32_swap_b32_e32 v185, v187
	global_store_dwordx4 v69, v[184:187], s[80:81] offset:96
	s_mov_b64 s[34:35], 0x2000
	s_ashr_i32 s31, s30, 31
	s_lshl_b64 s[30:31], s[30:31], 1
	s_add_i32 s24, s24, s64
	s_cmpk_gt_i32 s24, 0x27f
	s_cbranch_scc1 .LBB0_177

.LBB0_699:
	s_sub_u32 s77, s34, 0x1000
	s_lshr_b32 s77, s77, 12
	s_add_u32 s77, s77, 1
	s_cmp_lt_u32 s34, 0x1000
	s_cselect_b32 s77, 0, s77
	s_mul_i32 s77, s77, 0x6000
	s_add_u32 s68, s44, s77
	s_addc_u32 s69, s45, 0
	s_add_u32 s68, s68, 0xfa10600
	s_addc_u32 s69, s69, 0
	s_lshl_b32 s82, s34, 11
	s_add_u32 s80, s46, s82
	s_addc_u32 s81, s47, 0
	s_lshl_b32 s82, s30, 1
	s_add_u32 s80, s80, s82
	s_addc_u32 s81, s81, 0
	v_and_b32_e32 v0, 31, v200
	v_bfe_u32 v1, v200, 5, 1
	v_lshrrev_b32_e32 v2, 6, v200
	v_and_b32_e32 v68, 1, v2
	v_lshrrev_b32_e32 v69, 1, v2
	v_lshlrev_b32_e32 v70, 6, v68
	v_lshl_or_b32 v70, v1, 2, v70
	v_add_u32_e32 v71, s30, v70
	v_lshlrev_b32_e32 v71, 2, v71
	v_lshl_or_b32 v72, v69, 6, v0
	v_lshlrev_b32_e32 v73, 11, v72
	v_lshl_add_u32 v73, v70, 1, v73
	v_add_u32_e32 v74, 0x10000, v73
	v_lshlrev_b32_e32 v75, 11, v72
	v_lshl_add_u32 v75, v68, 7, v75
	v_lshl_add_u32 v75, v1, 4, v75
	v_add_u32_e32 v69, 0x10000, v75
	global_load_dwordx4 v[76:79], v71, s[42:43]
	global_load_dwordx4 v[80:83], v71, s[42:43] offset:32
	global_load_dwordx4 v[84:87], v71, s[42:43] offset:64
	global_load_dwordx4 v[88:91], v71, s[42:43] offset:96
	global_load_dwordx4 v[92:95], v71, s[42:43] offset:128
	global_load_dwordx4 v[96:99], v71, s[42:43] offset:160
	global_load_dwordx4 v[100:103], v71, s[42:43] offset:192
	global_load_dwordx4 v[104:107], v71, s[42:43] offset:224
	global_load_dwordx4 v[108:111], v71, s[68:69]
	global_load_dwordx4 v[112:115], v71, s[68:69] offset:32
	global_load_dwordx4 v[116:119], v71, s[68:69] offset:64
	global_load_dwordx4 v[120:123], v71, s[68:69] offset:96
	global_load_dwordx4 v[124:127], v71, s[68:69] offset:128
	global_load_dwordx4 v[128:131], v71, s[68:69] offset:160
	global_load_dwordx4 v[132:135], v71, s[68:69] offset:192
	global_load_dwordx4 v[136:139], v71, s[68:69] offset:224
	global_load_dwordx2 v[140:141], v73, s[80:81]
	global_load_dwordx2 v[142:143], v73, s[80:81] offset:16
	global_load_dwordx2 v[144:145], v73, s[80:81] offset:32
	global_load_dwordx2 v[146:147], v73, s[80:81] offset:48
	global_load_dwordx2 v[148:149], v73, s[80:81] offset:64
	global_load_dwordx2 v[150:151], v73, s[80:81] offset:80
	global_load_dwordx2 v[152:153], v73, s[80:81] offset:96
	global_load_dwordx2 v[154:155], v73, s[80:81] offset:112
	global_load_dwordx2 v[156:157], v74, s[80:81]
	global_load_dwordx2 v[158:159], v74, s[80:81] offset:16
	global_load_dwordx2 v[160:161], v74, s[80:81] offset:32
	global_load_dwordx2 v[162:163], v74, s[80:81] offset:48
	global_load_dwordx2 v[164:165], v74, s[80:81] offset:64
	global_load_dwordx2 v[166:167], v74, s[80:81] offset:80
	global_load_dwordx2 v[168:169], v74, s[80:81] offset:96
	global_load_dwordx2 v[170:171], v74, s[80:81] offset:112
	s_waitcnt vmcnt(14)
	v_cvt_f32_f16_e32 v188, v140
	v_cvt_f32_f16_sdwa v189, v140 dst_sel:DWORD dst_unused:UNUSED_PAD src0_sel:WORD_1
	v_cvt_f32_f16_e32 v190, v141
	v_cvt_f32_f16_sdwa v191, v141 dst_sel:DWORD dst_unused:UNUSED_PAD src0_sel:WORD_1
	v_cvt_f32_f16_e32 v192, v142
	v_cvt_f32_f16_sdwa v193, v142 dst_sel:DWORD dst_unused:UNUSED_PAD src0_sel:WORD_1
	v_cvt_f32_f16_e32 v194, v143
	v_cvt_f32_f16_sdwa v195, v143 dst_sel:DWORD dst_unused:UNUSED_PAD src0_sel:WORD_1
	v_pk_add_f32 v[52:53], v[52:53], v[76:77]
	v_pk_add_f32 v[54:55], v[54:55], v[78:79]
	v_pk_add_f32 v[56:57], v[56:57], v[80:81]
	v_pk_add_f32 v[58:59], v[58:59], v[82:83]
	v_pk_mul_f32 v[188:189], v[188:189], s[84:85] op_sel_hi:[1,0]
	v_pk_mul_f32 v[190:191], v[190:191], s[84:85] op_sel_hi:[1,0]
	v_pk_mul_f32 v[192:193], v[192:193], s[84:85] op_sel_hi:[1,0]
	v_pk_mul_f32 v[194:195], v[194:195], s[84:85] op_sel_hi:[1,0]
	v_pk_fma_f32 v[52:53], v[52:53], v[108:109], v[188:189]
	v_pk_fma_f32 v[54:55], v[54:55], v[110:111], v[190:191]
	v_pk_fma_f32 v[56:57], v[56:57], v[112:113], v[192:193]
	v_pk_fma_f32 v[58:59], v[58:59], v[114:115], v[194:195]
	v_cvt_pk_f16_f32 v172, v52, v53
	v_cvt_pk_f16_f32 v173, v54, v55
	v_cvt_pk_f16_f32 v174, v56, v57
	v_cvt_pk_f16_f32 v175, v58, v59
	s_nop 1
	v_permlane32_swap_b32_e32 v172, v174
	v_permlane32_swap_b32_e32 v173, v175
	global_store_dwordx4 v75, v[172:175], s[80:81]
	s_waitcnt vmcnt(13)
	v_cvt_f32_f16_e32 v188, v144
	v_cvt_f32_f16_sdwa v189, v144 dst_sel:DWORD dst_unused:UNUSED_PAD src0_sel:WORD_1
	v_cvt_f32_f16_e32 v190, v145
	v_cvt_f32_f16_sdwa v191, v145 dst_sel:DWORD dst_unused:UNUSED_PAD src0_sel:WORD_1
	v_cvt_f32_f16_e32 v192, v146
	v_cvt_f32_f16_sdwa v193, v146 dst_sel:DWORD dst_unused:UNUSED_PAD src0_sel:WORD_1
	v_cvt_f32_f16_e32 v194, v147
	v_cvt_f32_f16_sdwa v195, v147 dst_sel:DWORD dst_unused:UNUSED_PAD src0_sel:WORD_1
	v_pk_add_f32 v[60:61], v[60:61], v[84:85]
	v_pk_add_f32 v[62:63], v[62:63], v[86:87]
	v_pk_add_f32 v[64:65], v[64:65], v[88:89]
	v_pk_add_f32 v[66:67], v[66:67], v[90:91]
	v_pk_mul_f32 v[188:189], v[188:189], s[84:85] op_sel_hi:[1,0]
	v_pk_mul_f32 v[190:191], v[190:191], s[84:85] op_sel_hi:[1,0]
	v_pk_mul_f32 v[192:193], v[192:193], s[84:85] op_sel_hi:[1,0]
	v_pk_mul_f32 v[194:195], v[194:195], s[84:85] op_sel_hi:[1,0]
	v_pk_fma_f32 v[60:61], v[60:61], v[116:117], v[188:189]
	v_pk_fma_f32 v[62:63], v[62:63], v[118:119], v[190:191]
	v_pk_fma_f32 v[64:65], v[64:65], v[120:121], v[192:193]
	v_pk_fma_f32 v[66:67], v[66:67], v[122:123], v[194:195]
	v_cvt_pk_f16_f32 v184, v60, v61
	v_cvt_pk_f16_f32 v185, v62, v63
	v_cvt_pk_f16_f32 v186, v64, v65
	v_cvt_pk_f16_f32 v187, v66, v67
	s_nop 1
	v_permlane32_swap_b32_e32 v184, v186
	v_permlane32_swap_b32_e32 v185, v187
	global_store_dwordx4 v75, v[184:187], s[80:81] offset:32
	s_waitcnt vmcnt(12)
	v_cvt_f32_f16_e32 v188, v148
	v_cvt_f32_f16_sdwa v189, v148 dst_sel:DWORD dst_unused:UNUSED_PAD src0_sel:WORD_1
	v_cvt_f32_f16_e32 v190, v149
	v_cvt_f32_f16_sdwa v191, v149 dst_sel:DWORD dst_unused:UNUSED_PAD src0_sel:WORD_1
	v_cvt_f32_f16_e32 v192, v150
	v_cvt_f32_f16_sdwa v193, v150 dst_sel:DWORD dst_unused:UNUSED_PAD src0_sel:WORD_1
	v_cvt_f32_f16_e32 v194, v151
	v_cvt_f32_f16_sdwa v195, v151 dst_sel:DWORD dst_unused:UNUSED_PAD src0_sel:WORD_1
	v_pk_add_f32 v[36:37], v[36:37], v[92:93]
	v_pk_add_f32 v[38:39], v[38:39], v[94:95]
	v_pk_add_f32 v[40:41], v[40:41], v[96:97]
	v_pk_add_f32 v[42:43], v[42:43], v[98:99]
	v_pk_mul_f32 v[188:189], v[188:189], s[84:85] op_sel_hi:[1,0]
	v_pk_mul_f32 v[190:191], v[190:191], s[84:85] op_sel_hi:[1,0]
	v_pk_mul_f32 v[192:193], v[192:193], s[84:85] op_sel_hi:[1,0]
	v_pk_mul_f32 v[194:195], v[194:195], s[84:85] op_sel_hi:[1,0]
	v_pk_fma_f32 v[36:37], v[36:37], v[124:125], v[188:189]
	v_pk_fma_f32 v[38:39], v[38:39], v[126:127], v[190:191]
	v_pk_fma_f32 v[40:41], v[40:41], v[128:129], v[192:193]
	v_pk_fma_f32 v[42:43], v[42:43], v[130:131], v[194:195]
	v_cvt_pk_f16_f32 v172, v36, v37
	v_cvt_pk_f16_f32 v173, v38, v39
	v_cvt_pk_f16_f32 v174, v40, v41
	v_cvt_pk_f16_f32 v175, v42, v43
	s_nop 1
	v_permlane32_swap_b32_e32 v172, v174
	v_permlane32_swap_b32_e32 v173, v175
	global_store_dwordx4 v75, v[172:175], s[80:81] offset:64
	s_waitcnt vmcnt(11)
	v_cvt_f32_f16_e32 v188, v152
	v_cvt_f32_f16_sdwa v189, v152 dst_sel:DWORD dst_unused:UNUSED_PAD src0_sel:WORD_1
	v_cvt_f32_f16_e32 v190, v153
	v_cvt_f32_f16_sdwa v191, v153 dst_sel:DWORD dst_unused:UNUSED_PAD src0_sel:WORD_1
	v_cvt_f32_f16_e32 v192, v154
	v_cvt_f32_f16_sdwa v193, v154 dst_sel:DWORD dst_unused:UNUSED_PAD src0_sel:WORD_1
	v_cvt_f32_f16_e32 v194, v155
	v_cvt_f32_f16_sdwa v195, v155 dst_sel:DWORD dst_unused:UNUSED_PAD src0_sel:WORD_1
	v_pk_add_f32 v[44:45], v[44:45], v[100:101]
	v_pk_add_f32 v[46:47], v[46:47], v[102:103]
	v_pk_add_f32 v[48:49], v[48:49], v[104:105]
	v_pk_add_f32 v[50:51], v[50:51], v[106:107]
	v_pk_mul_f32 v[188:189], v[188:189], s[84:85] op_sel_hi:[1,0]
	v_pk_mul_f32 v[190:191], v[190:191], s[84:85] op_sel_hi:[1,0]
	v_pk_mul_f32 v[192:193], v[192:193], s[84:85] op_sel_hi:[1,0]
	v_pk_mul_f32 v[194:195], v[194:195], s[84:85] op_sel_hi:[1,0]
	v_pk_fma_f32 v[44:45], v[44:45], v[132:133], v[188:189]
	v_pk_fma_f32 v[46:47], v[46:47], v[134:135], v[190:191]
	v_pk_fma_f32 v[48:49], v[48:49], v[136:137], v[192:193]
	v_pk_fma_f32 v[50:51], v[50:51], v[138:139], v[194:195]
	v_cvt_pk_f16_f32 v184, v44, v45
	v_cvt_pk_f16_f32 v185, v46, v47
	v_cvt_pk_f16_f32 v186, v48, v49
	v_cvt_pk_f16_f32 v187, v50, v51
	s_nop 1
	v_permlane32_swap_b32_e32 v184, v186
	v_permlane32_swap_b32_e32 v185, v187
	global_store_dwordx4 v75, v[184:187], s[80:81] offset:96
	s_waitcnt vmcnt(10)
	v_cvt_f32_f16_e32 v188, v156
	v_cvt_f32_f16_sdwa v189, v156 dst_sel:DWORD dst_unused:UNUSED_PAD src0_sel:WORD_1
	v_cvt_f32_f16_e32 v190, v157
	v_cvt_f32_f16_sdwa v191, v157 dst_sel:DWORD dst_unused:UNUSED_PAD src0_sel:WORD_1
	v_cvt_f32_f16_e32 v192, v158
	v_cvt_f32_f16_sdwa v193, v158 dst_sel:DWORD dst_unused:UNUSED_PAD src0_sel:WORD_1
	v_cvt_f32_f16_e32 v194, v159
	v_cvt_f32_f16_sdwa v195, v159 dst_sel:DWORD dst_unused:UNUSED_PAD src0_sel:WORD_1
	v_pk_add_f32 v[20:21], v[20:21], v[76:77]
	v_pk_add_f32 v[22:23], v[22:23], v[78:79]
	v_pk_add_f32 v[24:25], v[24:25], v[80:81]
	v_pk_add_f32 v[26:27], v[26:27], v[82:83]
	v_pk_mul_f32 v[188:189], v[188:189], s[84:85] op_sel_hi:[1,0]
	v_pk_mul_f32 v[190:191], v[190:191], s[84:85] op_sel_hi:[1,0]
	v_pk_mul_f32 v[192:193], v[192:193], s[84:85] op_sel_hi:[1,0]
	v_pk_mul_f32 v[194:195], v[194:195], s[84:85] op_sel_hi:[1,0]
	v_pk_fma_f32 v[20:21], v[20:21], v[108:109], v[188:189]
	v_pk_fma_f32 v[22:23], v[22:23], v[110:111], v[190:191]
	v_pk_fma_f32 v[24:25], v[24:25], v[112:113], v[192:193]
	v_pk_fma_f32 v[26:27], v[26:27], v[114:115], v[194:195]
	v_cvt_pk_f16_f32 v172, v20, v21
	v_cvt_pk_f16_f32 v173, v22, v23
	v_cvt_pk_f16_f32 v174, v24, v25
	v_cvt_pk_f16_f32 v175, v26, v27
	s_nop 1
	v_permlane32_swap_b32_e32 v172, v174
	v_permlane32_swap_b32_e32 v173, v175
	global_store_dwordx4 v69, v[172:175], s[80:81]
	s_waitcnt vmcnt(9)
	v_cvt_f32_f16_e32 v188, v160
	v_cvt_f32_f16_sdwa v189, v160 dst_sel:DWORD dst_unused:UNUSED_PAD src0_sel:WORD_1
	v_cvt_f32_f16_e32 v190, v161
	v_cvt_f32_f16_sdwa v191, v161 dst_sel:DWORD dst_unused:UNUSED_PAD src0_sel:WORD_1
	v_cvt_f32_f16_e32 v192, v162
	v_cvt_f32_f16_sdwa v193, v162 dst_sel:DWORD dst_unused:UNUSED_PAD src0_sel:WORD_1
	v_cvt_f32_f16_e32 v194, v163
	v_cvt_f32_f16_sdwa v195, v163 dst_sel:DWORD dst_unused:UNUSED_PAD src0_sel:WORD_1
	v_pk_add_f32 v[28:29], v[28:29], v[84:85]
	v_pk_add_f32 v[30:31], v[30:31], v[86:87]
	v_pk_add_f32 v[32:33], v[32:33], v[88:89]
	v_pk_add_f32 v[34:35], v[34:35], v[90:91]
	v_pk_mul_f32 v[188:189], v[188:189], s[84:85] op_sel_hi:[1,0]
	v_pk_mul_f32 v[190:191], v[190:191], s[84:85] op_sel_hi:[1,0]
	v_pk_mul_f32 v[192:193], v[192:193], s[84:85] op_sel_hi:[1,0]
	v_pk_mul_f32 v[194:195], v[194:195], s[84:85] op_sel_hi:[1,0]
	v_pk_fma_f32 v[28:29], v[28:29], v[116:117], v[188:189]
	v_pk_fma_f32 v[30:31], v[30:31], v[118:119], v[190:191]
	v_pk_fma_f32 v[32:33], v[32:33], v[120:121], v[192:193]
	v_pk_fma_f32 v[34:35], v[34:35], v[122:123], v[194:195]
	v_cvt_pk_f16_f32 v184, v28, v29
	v_cvt_pk_f16_f32 v185, v30, v31
	v_cvt_pk_f16_f32 v186, v32, v33
	v_cvt_pk_f16_f32 v187, v34, v35
	s_nop 1
	v_permlane32_swap_b32_e32 v184, v186
	v_permlane32_swap_b32_e32 v185, v187
	global_store_dwordx4 v69, v[184:187], s[80:81] offset:32
	s_waitcnt vmcnt(8)
	v_cvt_f32_f16_e32 v188, v164
	v_cvt_f32_f16_sdwa v189, v164 dst_sel:DWORD dst_unused:UNUSED_PAD src0_sel:WORD_1
	v_cvt_f32_f16_e32 v190, v165
	v_cvt_f32_f16_sdwa v191, v165 dst_sel:DWORD dst_unused:UNUSED_PAD src0_sel:WORD_1
	v_cvt_f32_f16_e32 v192, v166
	v_cvt_f32_f16_sdwa v193, v166 dst_sel:DWORD dst_unused:UNUSED_PAD src0_sel:WORD_1
	v_cvt_f32_f16_e32 v194, v167
	v_cvt_f32_f16_sdwa v195, v167 dst_sel:DWORD dst_unused:UNUSED_PAD src0_sel:WORD_1
	v_pk_add_f32 v[4:5], v[4:5], v[92:93]
	v_pk_add_f32 v[6:7], v[6:7], v[94:95]
	v_pk_add_f32 v[8:9], v[8:9], v[96:97]
	v_pk_add_f32 v[10:11], v[10:11], v[98:99]
	v_pk_mul_f32 v[188:189], v[188:189], s[84:85] op_sel_hi:[1,0]
	v_pk_mul_f32 v[190:191], v[190:191], s[84:85] op_sel_hi:[1,0]
	v_pk_mul_f32 v[192:193], v[192:193], s[84:85] op_sel_hi:[1,0]
	v_pk_mul_f32 v[194:195], v[194:195], s[84:85] op_sel_hi:[1,0]
	v_pk_fma_f32 v[4:5], v[4:5], v[124:125], v[188:189]
	v_pk_fma_f32 v[6:7], v[6:7], v[126:127], v[190:191]
	v_pk_fma_f32 v[8:9], v[8:9], v[128:129], v[192:193]
	v_pk_fma_f32 v[10:11], v[10:11], v[130:131], v[194:195]
	v_cvt_pk_f16_f32 v172, v4, v5
	v_cvt_pk_f16_f32 v173, v6, v7
	v_cvt_pk_f16_f32 v174, v8, v9
	v_cvt_pk_f16_f32 v175, v10, v11
	s_nop 1
	v_permlane32_swap_b32_e32 v172, v174
	v_permlane32_swap_b32_e32 v173, v175
	global_store_dwordx4 v69, v[172:175], s[80:81] offset:64
	s_waitcnt vmcnt(7)
	v_cvt_f32_f16_e32 v188, v168
	v_cvt_f32_f16_sdwa v189, v168 dst_sel:DWORD dst_unused:UNUSED_PAD src0_sel:WORD_1
	v_cvt_f32_f16_e32 v190, v169
	v_cvt_f32_f16_sdwa v191, v169 dst_sel:DWORD dst_unused:UNUSED_PAD src0_sel:WORD_1
	v_cvt_f32_f16_e32 v192, v170
	v_cvt_f32_f16_sdwa v193, v170 dst_sel:DWORD dst_unused:UNUSED_PAD src0_sel:WORD_1
	v_cvt_f32_f16_e32 v194, v171
	v_cvt_f32_f16_sdwa v195, v171 dst_sel:DWORD dst_unused:UNUSED_PAD src0_sel:WORD_1
	v_pk_add_f32 v[12:13], v[12:13], v[100:101]
	v_pk_add_f32 v[14:15], v[14:15], v[102:103]
	v_pk_add_f32 v[16:17], v[16:17], v[104:105]
	v_pk_add_f32 v[18:19], v[18:19], v[106:107]
	v_pk_mul_f32 v[188:189], v[188:189], s[84:85] op_sel_hi:[1,0]
	v_pk_mul_f32 v[190:191], v[190:191], s[84:85] op_sel_hi:[1,0]
	v_pk_mul_f32 v[192:193], v[192:193], s[84:85] op_sel_hi:[1,0]
	v_pk_mul_f32 v[194:195], v[194:195], s[84:85] op_sel_hi:[1,0]
	v_pk_fma_f32 v[12:13], v[12:13], v[132:133], v[188:189]
	v_pk_fma_f32 v[14:15], v[14:15], v[134:135], v[190:191]
	v_pk_fma_f32 v[16:17], v[16:17], v[136:137], v[192:193]
	v_pk_fma_f32 v[18:19], v[18:19], v[138:139], v[194:195]
	v_cvt_pk_f16_f32 v184, v12, v13
	v_cvt_pk_f16_f32 v185, v14, v15
	v_cvt_pk_f16_f32 v186, v16, v17
	v_cvt_pk_f16_f32 v187, v18, v19
	s_nop 1
	v_permlane32_swap_b32_e32 v184, v186
	v_permlane32_swap_b32_e32 v185, v187
	global_store_dwordx4 v69, v[184:187], s[80:81] offset:96
	s_mov_b64 s[34:35], 0xfa10600
	s_ashr_i32 s31, s30, 31
	s_lshl_b64 s[30:31], s[30:31], 1
	s_add_i32 s24, s24, s64
	s_cmpk_gt_i32 s24, 0x27f
	s_cbranch_scc1 .LBB0_759
